# split-update version with helper priority raised only during the PREP passes
# baseline (speedup 1.0000x reference)
.Lmy_f_nol34:
	s_waitcnt lgkmcnt(0)
	s_setprio 0
	s_bfe_u32 s96, s62, 0x20006
	s_lshl_b32 s100, s96, 11
	v_lshl_add_u32 v72, v224, 2, s100
	s_and_b32 s97, s96, 1
	s_mul_i32 s97, s97, 0x2700
	s_mov_b32 s101, 0x1c000
	s_mov_b32 s100, 0x6100
	s_bitcmp0_b32 s65, 0
	s_cselect_b32 s101, 0xe000, s101
	s_cselect_b32 s100, 0x4e00, s100
	s_cmp_gt_u32 s96, 1
	s_cselect_b32 s100, s100, 0
	s_add_i32 s97, s97, s101
	s_add_i32 s97, s97, s100
	ds_read_b32 v80, v72
	ds_read_b32 v81, v72 offset:256
	ds_read_b32 v82, v72 offset:512
	ds_read_b32 v83, v72 offset:768
	ds_read_b32 v84, v72 offset:1024
	ds_read_b32 v85, v72 offset:1280
	ds_read_b32 v86, v72 offset:1536
	ds_read_b32 v87, v72 offset:1792
	ds_read_b32 v88, v72 offset:8192
	ds_read_b32 v89, v72 offset:8448
	ds_read_b32 v90, v72 offset:8704
	ds_read_b32 v91, v72 offset:8960
	ds_read_b32 v92, v72 offset:9216
	ds_read_b32 v93, v72 offset:9472
	ds_read_b32 v94, v72 offset:9728
	ds_read_b32 v95, v72 offset:9984
	ds_read_b32 v96, v72 offset:32768
	ds_read_b32 v97, v72 offset:33024
	ds_read_b32 v98, v72 offset:33280
	ds_read_b32 v99, v72 offset:33536
	ds_read_b32 v100, v72 offset:33792
	ds_read_b32 v101, v72 offset:34048
	ds_read_b32 v102, v72 offset:34304
	ds_read_b32 v103, v72 offset:34560
	v_and_b32_e32 v74, 3, v224
	v_bfe_u32 v75, v224, 2, 2
	v_lshrrev_b32_e32 v76, 4, v224
	v_lshlrev_b32_e32 v74, 2, v74
	v_lshl_add_u32 v74, v75, 8, v74
	v_lshl_add_u32 v74, v76, 10, v74
	s_add_i32 s100, s97, 0x0
	v_add_u32_e32 v74, s100, v74
	v_xor_b32_e32 v76, 0, v75
	v_xor_b32_e32 v77, 1, v75
	v_xor_b32_e32 v78, 2, v75
	v_xor_b32_e32 v79, 3, v75
	v_lshl_add_u32 v76, v76, 4, v74
	v_lshl_add_u32 v77, v77, 4, v74
	v_lshl_add_u32 v78, v78, 4, v74
	v_lshl_add_u32 v79, v79, 4, v74
	s_waitcnt lgkmcnt(15)
	v_mov_b32_e32 v104, v80
	v_mul_f32_e32 v105, v104, v81
	v_mul_f32_e32 v106, v105, v82
	v_mul_f32_e32 v107, v106, v83
	v_mul_f32_e32 v108, v107, v84
	v_mul_f32_e32 v109, v108, v85
	v_mul_f32_e32 v110, v109, v86
	v_mul_f32_e32 v111, v110, v87
	v_mov_b32_e32 v112, v88
	s_waitcnt lgkmcnt(14)
	v_mul_f32_e32 v113, v104, v89
	s_waitcnt lgkmcnt(13)
	v_mul_f32_e32 v114, v105, v90
	s_waitcnt lgkmcnt(12)
	v_mul_f32_e32 v115, v106, v91
	s_waitcnt lgkmcnt(11)
	v_mul_f32_e32 v116, v107, v92
	s_waitcnt lgkmcnt(10)
	v_mul_f32_e32 v117, v108, v93
	s_waitcnt lgkmcnt(9)
	v_mul_f32_e32 v118, v109, v94
	s_waitcnt lgkmcnt(8)
	v_mul_f32_e32 v119, v110, v95
	s_waitcnt lgkmcnt(7)
	v_mul_f32_e32 v120, v104, v96
	s_waitcnt lgkmcnt(6)
	v_mul_f32_e32 v121, v105, v97
	s_waitcnt lgkmcnt(5)
	v_mul_f32_e32 v122, v106, v98
	s_waitcnt lgkmcnt(4)
	v_mul_f32_e32 v123, v107, v99
	s_waitcnt lgkmcnt(3)
	v_mul_f32_e32 v124, v108, v100
	s_waitcnt lgkmcnt(2)
	v_mul_f32_e32 v125, v109, v101
	s_waitcnt lgkmcnt(1)
	v_mul_f32_e32 v126, v110, v102
	s_waitcnt lgkmcnt(0)
	v_mul_f32_e32 v127, v111, v103
	ds_write_b32 v76, v112
	ds_write_b32 v77, v113
	ds_write_b32 v78, v114
	ds_write_b32 v79, v115
	ds_write_b32 v76, v116 offset:64
	ds_write_b32 v77, v117 offset:64
	ds_write_b32 v78, v118 offset:64
	ds_write_b32 v79, v119 offset:64
	ds_write_b32 v76, v120 offset:128
	ds_write_b32 v77, v121 offset:128
	ds_write_b32 v78, v122 offset:128
	ds_write_b32 v79, v123 offset:128
	ds_write_b32 v76, v124 offset:192
	ds_write_b32 v77, v125 offset:192
	ds_write_b32 v78, v126 offset:192
	ds_write_b32 v79, v127 offset:192

.Lmy_ck_drE_h:
	s_waitcnt lgkmcnt(0)
	s_bfe_u32 s96, s62, 0x20006
	s_and_b32 s97, s96, 1
	s_mul_i32 s97, s97, 0x2700
	s_mov_b32 s101, 0x1c000
	s_mov_b32 s100, 0x6100
	s_bitcmp0_b32 s65, 0
	s_cselect_b32 s101, 0xe000, s101
	s_cselect_b32 s100, 0x4e00, s100
	s_cmp_gt_u32 s96, 1
	s_cselect_b32 s100, s100, 0
	s_add_i32 s97, s97, s101
	s_add_i32 s97, s97, s100
	s_mov_b32 s96, s97
	v_and_b32_e32 v72, 3, v233
	v_lshrrev_b32_e32 v73, 2, v233
	v_lshlrev_b32_e32 v72, 2, v72
	v_lshl_add_u32 v72, v73, 8, v72
	v_lshl_add_u32 v72, v234, 6, v72
	s_add_i32 s97, s96, 0x1000
	v_add_u32_e32 v78, s97, v72
	v_xor_b32_e32 v79, v224, v234
	v_lshl_add_u32 v79, v79, 4, s96
	ds_read_b128 v[96:99], v79
	ds_read_b128 v[100:103], v79 offset:1024
	ds_read_b128 v[104:107], v79 offset:2048
	ds_read_b128 v[108:111], v79 offset:3072
	ds_read_b32 v80, v78
	ds_read_b32 v81, v78 offset:16
	ds_read_b32 v82, v78 offset:32
	ds_read_b32 v83, v78 offset:48
	ds_read_b32 v84, v78 offset:1024
	ds_read_b32 v85, v78 offset:1040
	ds_read_b32 v86, v78 offset:1056
	ds_read_b32 v87, v78 offset:1072
	ds_read_b32 v88, v78 offset:2048
	ds_read_b32 v89, v78 offset:2064
	ds_read_b32 v90, v78 offset:2080
	ds_read_b32 v91, v78 offset:2096
	ds_read_b32 v92, v78 offset:3072
	ds_read_b32 v93, v78 offset:3088
	ds_read_b32 v94, v78 offset:3104
	ds_read_b32 v95, v78 offset:3120
	v_lshl_add_u32 v74, v224, 2, s96
	ds_write_b32 v74, v235 offset:9728
	v_add_u32_e32 v75, -1, v233
	v_mov_b32_e32 v76, -1
	v_cndmask_b32_e64 v75, v76, v75, s[98:99]
	v_cmp_lt_u32_e64 s[100:101], 7, v233
	v_add_u32_e32 v76, -8, v233
	v_and_b32_e32 v77, 1, v234
	v_cndmask_b32_e64 v75, v75, v76, s[100:101]
	v_lshlrev_b32_e32 v77, 2, v77
	v_sub_u32_e32 v76, v75, v77
	v_lshlrev_b32_e32 v77, 2, v234
	v_sub_u32_e32 v77, v233, v77
	v_add_u32_e32 v77, -1, v77
	s_waitcnt lgkmcnt(15)
	v_mfma_f32_16x16x4_f32 v[244:247], v80, v96, 0
	v_mfma_f32_16x16x4_f32 v[240:243], v81, v97, 0
	s_waitcnt lgkmcnt(14)
	v_mfma_f32_16x16x4_f32 v[244:247], v82, v98, v[244:247]
	s_waitcnt lgkmcnt(13)
	v_mfma_f32_16x16x4_f32 v[240:243], v83, v99, v[240:243]
	s_waitcnt lgkmcnt(12)
	v_mfma_f32_16x16x4_f32 v[244:247], v84, v100, v[244:247]
	s_waitcnt lgkmcnt(11)
	v_mfma_f32_16x16x4_f32 v[240:243], v85, v101, v[240:243]
	s_waitcnt lgkmcnt(10)
	v_mfma_f32_16x16x4_f32 v[244:247], v86, v102, v[244:247]
	s_waitcnt lgkmcnt(9)
	v_mfma_f32_16x16x4_f32 v[240:243], v87, v103, v[240:243]
	s_waitcnt lgkmcnt(8)
	v_mfma_f32_16x16x4_f32 v[244:247], v88, v104, v[244:247]
	s_waitcnt lgkmcnt(7)
	v_mfma_f32_16x16x4_f32 v[240:243], v89, v105, v[240:243]
	s_waitcnt lgkmcnt(6)
	v_mfma_f32_16x16x4_f32 v[244:247], v90, v106, v[244:247]
	s_waitcnt lgkmcnt(5)
	v_mfma_f32_16x16x4_f32 v[240:243], v91, v107, v[240:243]
	s_waitcnt lgkmcnt(4)
	v_mfma_f32_16x16x4_f32 v[244:247], v92, v108, v[244:247]
	s_waitcnt lgkmcnt(3)
	v_mfma_f32_16x16x4_f32 v[240:243], v93, v109, v[240:243]
	s_waitcnt lgkmcnt(2)
	v_mfma_f32_16x16x4_f32 v[244:247], v94, v110, v[244:247]
	s_waitcnt lgkmcnt(1)
	v_mfma_f32_16x16x4_f32 v[240:243], v95, v111, v[240:243]
	s_nop 9
	v_add_f32_e32 v244, v244, v240
	v_add_f32_e32 v245, v245, v241
	v_add_f32_e32 v246, v246, v242
	v_add_f32_e32 v247, v247, v243
	v_cmp_le_i32_e64 s[96:97], 0, v76
	v_cmp_le_i32_e64 s[100:101], 1, v76
	s_nop 0
	v_cndmask_b32_e64 v128, 0, v244, s[96:97]
	v_cndmask_b32_e64 v129, 0, v245, s[100:101]
	v_cmp_le_i32_e64 s[96:97], 2, v76
	v_cmp_le_i32_e64 s[100:101], 3, v76
	s_nop 0
	v_cndmask_b32_e64 v130, 0, v246, s[96:97]
	v_cndmask_b32_e64 v131, 0, v247, s[100:101]
	s_bfe_u32 s96, s62, 0x20006
	s_and_b32 s97, s96, 1
	s_mul_i32 s97, s97, 0x2700
	s_mov_b32 s101, 0x1c000
	s_mov_b32 s100, 0x6100
	s_bitcmp0_b32 s65, 0
	s_cselect_b32 s101, 0xe000, s101
	s_cselect_b32 s100, 0x4e00, s100
	s_cmp_gt_u32 s96, 1
	s_cselect_b32 s100, s100, 0
	s_add_i32 s97, s97, s101
	s_add_i32 s97, s97, s100
	v_xor_b32_e32 v74, v224, v234
	v_lshl_add_u32 v74, v74, 4, s97
	ds_write_b128 v74, v[128:131] offset:8448
	v_lshlrev_b32_e32 v75, 7, v234
	v_lshl_add_u32 v75, v233, 2, v75
	v_add_u32_e32 v75, s97, v75
	v_cmp_le_i32_e64 s[96:97], 0, v77
	v_cmp_le_i32_e64 s[100:101], 1, v77
	s_nop 0
	v_cndmask_b32_e64 v132, 0, v244, s[96:97]
	v_cndmask_b32_e64 v133, 0, v245, s[100:101]
	v_cmp_le_i32_e64 s[96:97], 2, v77
	v_cmp_le_i32_e64 s[100:101], 3, v77
	s_nop 0
	v_cndmask_b32_e64 v134, 0, v246, s[96:97]
	v_cndmask_b32_e64 v135, 0, v247, s[100:101]
	s_mov_b64 exec, 0x00ff00ff
	ds_write_b32 v75, v132 offset:9472
	ds_write_b32 v75, v133 offset:9504
	ds_write_b32 v75, v134 offset:9536
	ds_write_b32 v75, v135 offset:9568
	s_mov_b64 exec, -1
	s_branch .LBB0_655
	s_nop 0
	s_nop 0
	s_nop 0
	s_nop 0
	s_nop 0
	s_nop 0
	s_nop 0
	s_nop 0
	s_nop 0
	s_nop 0
	s_nop 0
	s_nop 0
	s_nop 0
	s_nop 0
	s_nop 0
	s_nop 0
	s_nop 0
	s_nop 0
	s_nop 0
	s_nop 0
	s_nop 0
	s_nop 0
	s_nop 0
	s_nop 0
	s_nop 0
	s_nop 0
	s_nop 0
	s_nop 0
	s_nop 0
	s_nop 0
	s_nop 0
	s_nop 0
	s_nop 0
	s_nop 0
	s_nop 0
	s_nop 0
	s_nop 0
	s_nop 0
	s_nop 0
	s_nop 0
	s_nop 0
	s_nop 0
